# stack6 plus DPP adds for the xor-1/2/4/8 steps of the seam_rows wave sums (7 reductions)
# baseline (speedup 1.0000x reference)
; template <bool HAS_M, bool WRITE_X, bool WRITE_HN>
; __device__ __forceinline__ void seam_rows(const float* xin, const bf16_t* mb, const float* gpost, const float* gpre, float* xout, bf16_t* hn, int gw, int NGW, int lane) {
;     for (int row = gw; row < M; row += NGW) {
;         const size_t ro = (size_t)row * DM + lane * 8;
;         float v[32];
; #pragma unroll
;         for (int s = 0; s < 4; ++s) ld8f(xin + ro + s * 512, v + s * 8);
;         if (HAS_M) {
;             float mv[32]; float ss = 0.f;
; #pragma unroll
;             for (int s = 0; s < 4; ++s) unpack8(*(const u32x4*)(mb + ro + s * 512), mv + s * 8);
; #pragma unroll
;             for (int i = 0; i < 32; ++i) ss += mv[i] * mv[i];
;             const float r1 = rsqrtf(wave_sum(ss) * (1.f / 2048.f) + 1e-6f);
; #pragma unroll
;             for (int s = 0; s < 4; ++s) { float g[8]; ld8f(gpost + s * 512 + lane * 8, g);
; #pragma unroll
;                 for (int i = 0; i < 8; ++i) v[s * 8 + i] += mv[s * 8 + i] * r1 * g[i]; }
;         }
;         if (WRITE_X) {
; #pragma unroll
;             for (int s = 0; s < 4; ++s) { *(f32x4*)(xout + ro + s * 512) = (f32x4){v[s * 8], v[s * 8 + 1], v[s * 8 + 2], v[s * 8 + 3]}; *(f32x4*)(xout + ro + s * 512 + 4) = (f32x4){v[s * 8 + 4], v[s * 8 + 5], v[s * 8 + 6], v[s * 8 + 7]}; }
;         }
.LBB0_20:
	global_load_dwordx4 v[76:79], v[88:89], off offset:-2048
	global_load_dwordx4 v[72:75], v[88:89], off offset:-1024
	global_load_dwordx4 v[68:71], v[88:89], off
	global_load_dwordx4 v[64:67], v[88:89], off offset:1024
	global_load_dwordx4 v[20:23], v[86:87], off offset:-4080
	global_load_dwordx4 v[28:31], v[86:87], off offset:-4096
	global_load_dwordx4 v[12:15], v[86:87], off offset:-2032
	global_load_dwordx4 v[24:27], v[86:87], off offset:-2048
	global_load_dwordx4 v[4:7], v[86:87], off offset:16
	global_load_dwordx4 v[16:19], v[86:87], off
	global_load_dwordx4 v[0:3], v[86:87], off offset:2064
	global_load_dwordx4 v[8:11], v[86:87], off offset:2048
	global_load_dwordx4 v[32:35], v[80:81], off offset:16
	global_load_dwordx4 v[36:39], v[80:81], off
	global_load_dwordx4 v[40:43], v[80:81], off offset:2064
	global_load_dwordx4 v[44:47], v[80:81], off offset:2048
	global_load_dwordx4 v[48:51], v[82:83], off offset:16
	global_load_dwordx4 v[52:55], v[82:83], off
	global_load_dwordx4 v[56:59], v[84:85], off offset:16
	global_load_dwordx4 v[60:63], v[84:85], off
	s_add_i32 s2, s2, s16
	v_lshl_add_u64 v[88:89], v[88:89], 0, s[40:41]
	s_cmpk_lt_i32 s2, 0x4000
	s_waitcnt vmcnt(19)
	v_lshlrev_b32_e32 v96, 16, v76
	v_and_b32_e32 v97, 0xffff0000, v76
	v_lshlrev_b32_e32 v76, 16, v77
	v_and_b32_e32 v77, 0xffff0000, v77
	v_pk_mul_f32 v[112:113], v[96:97], v[96:97]
	v_pk_mul_f32 v[114:115], v[76:77], v[76:77]
	v_add_f32_e32 v112, v112, v113
	v_lshlrev_b32_e32 v98, 16, v78
	v_and_b32_e32 v99, 0xffff0000, v78
	v_add_f32_e32 v112, v114, v112
	v_pk_mul_f32 v[116:117], v[98:99], v[98:99]
	v_add_f32_e32 v112, v115, v112
	v_lshlrev_b32_e32 v78, 16, v79
	v_and_b32_e32 v79, 0xffff0000, v79
	v_add_f32_e32 v112, v116, v112
	v_pk_mul_f32 v[118:119], v[78:79], v[78:79]
	v_add_f32_e32 v112, v117, v112
	s_waitcnt vmcnt(18)
	v_lshlrev_b32_e32 v100, 16, v72
	v_and_b32_e32 v101, 0xffff0000, v72
	v_add_f32_e32 v112, v118, v112
	v_pk_mul_f32 v[120:121], v[100:101], v[100:101]
	v_add_f32_e32 v112, v119, v112
	v_lshlrev_b32_e32 v72, 16, v73
	v_and_b32_e32 v73, 0xffff0000, v73
	v_add_f32_e32 v112, v120, v112
	v_pk_mul_f32 v[122:123], v[72:73], v[72:73]
	v_add_f32_e32 v112, v121, v112
	v_lshlrev_b32_e32 v102, 16, v74
	v_and_b32_e32 v103, 0xffff0000, v74
	v_add_f32_e32 v112, v122, v112
	v_pk_mul_f32 v[124:125], v[102:103], v[102:103]
	v_add_f32_e32 v112, v123, v112
	v_lshlrev_b32_e32 v74, 16, v75
	v_and_b32_e32 v75, 0xffff0000, v75
	v_add_f32_e32 v112, v124, v112
	v_pk_mul_f32 v[126:127], v[74:75], v[74:75]
	v_add_f32_e32 v112, v125, v112
	s_waitcnt vmcnt(17)
	v_lshlrev_b32_e32 v104, 16, v68
	v_and_b32_e32 v105, 0xffff0000, v68
	v_add_f32_e32 v112, v126, v112
	v_pk_mul_f32 v[130:131], v[104:105], v[104:105]
	v_add_f32_e32 v112, v127, v112
	v_lshlrev_b32_e32 v68, 16, v69
	v_and_b32_e32 v69, 0xffff0000, v69
	v_add_f32_e32 v112, v130, v112
	v_pk_mul_f32 v[132:133], v[68:69], v[68:69]
	v_add_f32_e32 v112, v131, v112
	v_lshlrev_b32_e32 v106, 16, v70
	v_and_b32_e32 v107, 0xffff0000, v70
	v_add_f32_e32 v112, v132, v112
	v_pk_mul_f32 v[134:135], v[106:107], v[106:107]
	v_add_f32_e32 v112, v133, v112
	v_lshlrev_b32_e32 v70, 16, v71
	v_and_b32_e32 v71, 0xffff0000, v71
	v_add_f32_e32 v112, v134, v112
	v_pk_mul_f32 v[136:137], v[70:71], v[70:71]
	v_add_f32_e32 v112, v135, v112
	s_waitcnt vmcnt(16)
; template <bool HAS_M, bool WRITE_X, bool WRITE_HN>
; __device__ __forceinline__ void seam_rows(const float* xin, const bf16_t* mb, const float* gpost, const float* gpre, float* xout, bf16_t* hn, int gw, int NGW, int lane) {
;     for (int row = gw; row < M; row += NGW) {
;         const size_t ro = (size_t)row * DM + lane * 8;
;         float v[32];
; #pragma unroll
;         for (int s = 0; s < 4; ++s) ld8f(xin + ro + s * 512, v + s * 8);
;         if (HAS_M) {
;             float mv[32]; float ss = 0.f;
; #pragma unroll
;             for (int s = 0; s < 4; ++s) unpack8(*(const u32x4*)(mb + ro + s * 512), mv + s * 8);
; #pragma unroll
;             for (int i = 0; i < 32; ++i) ss += mv[i] * mv[i];
;             const float r1 = rsqrtf(wave_sum(ss) * (1.f / 2048.f) + 1e-6f);
; #pragma unroll
;             for (int s = 0; s < 4; ++s) { float g[8]; ld8f(gpost + s * 512 + lane * 8, g);
; #pragma unroll
;                 for (int i = 0; i < 8; ++i) v[s * 8 + i] += mv[s * 8 + i] * r1 * g[i]; }
;         }
;         if (WRITE_X) {
; #pragma unroll
;             for (int s = 0; s < 4; ++s) { *(f32x4*)(xout + ro + s * 512) = (f32x4){v[s * 8], v[s * 8 + 1], v[s * 8 + 2], v[s * 8 + 3]}; *(f32x4*)(xout + ro + s * 512 + 4) = (f32x4){v[s * 8 + 4], v[s * 8 + 5], v[s * 8 + 6], v[s * 8 + 7]}; }
;         }
	v_lshlrev_b32_e32 v108, 16, v64
	v_and_b32_e32 v109, 0xffff0000, v64
	v_add_f32_e32 v112, v136, v112
	v_pk_mul_f32 v[138:139], v[108:109], v[108:109]
	v_add_f32_e32 v112, v137, v112
	v_lshlrev_b32_e32 v64, 16, v65
	v_and_b32_e32 v65, 0xffff0000, v65
	v_add_f32_e32 v112, v138, v112
	v_pk_mul_f32 v[140:141], v[64:65], v[64:65]
	v_add_f32_e32 v112, v139, v112
	v_lshlrev_b32_e32 v110, 16, v66
	v_and_b32_e32 v111, 0xffff0000, v66
	v_add_f32_e32 v112, v140, v112
	v_pk_mul_f32 v[142:143], v[110:111], v[110:111]
	v_add_f32_e32 v112, v141, v112
	v_lshlrev_b32_e32 v66, 16, v67
	v_and_b32_e32 v67, 0xffff0000, v67
	v_add_f32_e32 v112, v142, v112
	v_pk_mul_f32 v[144:145], v[66:67], v[66:67]
	v_add_f32_e32 v112, v143, v112
	v_add_f32_e32 v112, v144, v112
	v_add_f32_e32 v112, v145, v112
	s_nop 1
	v_add_f32_dpp v112, v112, v112 quad_perm:[1,0,3,2] row_mask:0xf bank_mask:0xf
	s_nop 1
	v_add_f32_dpp v112, v112, v112 quad_perm:[2,3,0,1] row_mask:0xf bank_mask:0xf
	s_nop 1
	v_add_f32_dpp v112, v112, v112 row_half_mirror row_mask:0xf bank_mask:0xf
	s_nop 1
	v_add_f32_dpp v112, v112, v112 row_mirror row_mask:0xf bank_mask:0xf
	ds_bpermute_b32 v113, v94, v112
	s_waitcnt lgkmcnt(0)
	v_add_f32_e32 v112, v112, v113
	ds_bpermute_b32 v113, v95, v112
	s_waitcnt lgkmcnt(0)
	v_add_f32_e32 v112, v112, v113
	v_fmamk_f32 v112, v112, 0x3a000000, v209
	v_mul_f32_e32 v113, 0x4b800000, v112
	v_cmp_gt_f32_e32 vcc, s15, v112
	s_nop 1
	v_cndmask_b32_e32 v112, v112, v113, vcc
	v_rsq_f32_e32 v112, v112
	s_nop 0
	v_mul_f32_e32 v113, 0x45800000, v112
	v_cndmask_b32_e32 v112, v112, v113, vcc
	v_pk_mul_f32 v[96:97], v[112:113], v[96:97] op_sel_hi:[0,1]
	v_pk_mul_f32 v[76:77], v[112:113], v[76:77] op_sel_hi:[0,1]
	v_pk_mul_f32 v[98:99], v[112:113], v[98:99] op_sel_hi:[0,1]
	v_pk_mul_f32 v[78:79], v[112:113], v[78:79] op_sel_hi:[0,1]
	v_pk_mul_f32 v[100:101], v[112:113], v[100:101] op_sel_hi:[0,1]
	v_pk_mul_f32 v[72:73], v[112:113], v[72:73] op_sel_hi:[0,1]
	v_pk_mul_f32 v[102:103], v[112:113], v[102:103] op_sel_hi:[0,1]
	v_pk_mul_f32 v[74:75], v[112:113], v[74:75] op_sel_hi:[0,1]
	v_pk_mul_f32 v[104:105], v[112:113], v[104:105] op_sel_hi:[0,1]
	v_pk_mul_f32 v[68:69], v[112:113], v[68:69] op_sel_hi:[0,1]
	v_pk_mul_f32 v[106:107], v[112:113], v[106:107] op_sel_hi:[0,1]
	v_pk_mul_f32 v[70:71], v[112:113], v[70:71] op_sel_hi:[0,1]
	v_pk_mul_f32 v[108:109], v[112:113], v[108:109] op_sel_hi:[0,1]
	v_pk_mul_f32 v[64:65], v[112:113], v[64:65] op_sel_hi:[0,1]
	v_pk_mul_f32 v[110:111], v[112:113], v[110:111] op_sel_hi:[0,1]
	v_pk_mul_f32 v[66:67], v[112:113], v[66:67] op_sel_hi:[0,1]
	s_waitcnt vmcnt(6)
	v_pk_fma_f32 v[30:31], v[38:39], v[76:77], v[30:31]
	v_pk_fma_f32 v[28:29], v[36:37], v[96:97], v[28:29]
	v_pk_fma_f32 v[22:23], v[34:35], v[78:79], v[22:23]
	v_pk_fma_f32 v[20:21], v[32:33], v[98:99], v[20:21]
	s_waitcnt vmcnt(4)
	v_pk_fma_f32 v[26:27], v[46:47], v[72:73], v[26:27]
	v_pk_fma_f32 v[24:25], v[44:45], v[100:101], v[24:25]
	v_pk_fma_f32 v[14:15], v[42:43], v[74:75], v[14:15]
	v_pk_fma_f32 v[12:13], v[40:41], v[102:103], v[12:13]
	s_waitcnt vmcnt(2)
	v_pk_fma_f32 v[18:19], v[54:55], v[68:69], v[18:19]
	v_pk_fma_f32 v[16:17], v[52:53], v[104:105], v[16:17]
	v_pk_fma_f32 v[6:7], v[50:51], v[70:71], v[6:7]
	v_pk_fma_f32 v[4:5], v[48:49], v[106:107], v[4:5]
	s_waitcnt vmcnt(0)
	v_pk_fma_f32 v[10:11], v[62:63], v[64:65], v[10:11]
	v_pk_fma_f32 v[8:9], v[60:61], v[108:109], v[8:9]
	v_pk_fma_f32 v[2:3], v[58:59], v[66:67], v[2:3]
	v_pk_fma_f32 v[0:1], v[56:57], v[110:111], v[0:1]
	global_store_dwordx4 v[86:87], v[28:31], off offset:-4096
	global_store_dwordx4 v[86:87], v[20:23], off offset:-4080
	global_store_dwordx4 v[86:87], v[24:27], off offset:-2048
	global_store_dwordx4 v[86:87], v[12:15], off offset:-2032
	global_store_dwordx4 v[86:87], v[16:19], off
	global_store_dwordx4 v[86:87], v[4:7], off offset:16
	global_store_dwordx4 v[86:87], v[8:11], off offset:2048
	global_store_dwordx4 v[86:87], v[0:3], off offset:2064
	v_lshl_add_u64 v[86:87], v[86:87], 0, s[30:31]
	s_cbranch_scc1 .LBB0_20
	s_mov_b32 s37, 0x14000
	s_mov_b32 s40, 0x18000
	s_mov_b32 s41, 0x8000
	s_mov_b64 s[26:27], 0x1000

; template <bool HAS_M, bool WRITE_X, bool WRITE_HN>
; __device__ __forceinline__ void seam_rows(const float* xin, const bf16_t* mb, const float* gpost, const float* gpre, float* xout, bf16_t* hn, int gw, int NGW, int lane) {
;     for (int row = gw; row < M; row += NGW) {
;         const size_t ro = (size_t)row * DM + lane * 8;
;         float v[32];
; #pragma unroll
;         for (int s = 0; s < 4; ++s) ld8f(xin + ro + s * 512, v + s * 8);
;         if (HAS_M) {
;             float mv[32]; float ss = 0.f;
; #pragma unroll
;             for (int s = 0; s < 4; ++s) unpack8(*(const u32x4*)(mb + ro + s * 512), mv + s * 8);
; #pragma unroll
;             for (int i = 0; i < 32; ++i) ss += mv[i] * mv[i];
;             const float r1 = rsqrtf(wave_sum(ss) * (1.f / 2048.f) + 1e-6f);
; #pragma unroll
;             for (int s = 0; s < 4; ++s) { float g[8]; ld8f(gpost + s * 512 + lane * 8, g);
; #pragma unroll
;                 for (int i = 0; i < 8; ++i) v[s * 8 + i] += mv[s * 8 + i] * r1 * g[i]; }
.LBB0_80:
	v_add_co_u32_e32 v0, vcc, 0xec000000, v26
	s_add_i32 s10, s10, s16
	s_nop 0
	v_addc_co_u32_e32 v1, vcc, -1, v27, vcc
	global_load_dwordx4 v[8:11], v[0:1], off
	v_add_co_u32_e32 v0, vcc, 0xec001000, v26
	s_cmpk_gt_i32 s10, 0x3fff
	s_nop 0
	v_addc_co_u32_e32 v1, vcc, -1, v27, vcc
	global_load_dwordx4 v[34:37], v[0:1], off offset:-3072
	global_load_dwordx4 v[38:41], v[0:1], off offset:-2048
	global_load_dwordx4 v[42:45], v[0:1], off offset:-1024
	global_load_dwordx4 v[46:49], v[24:25], off offset:-4080
	global_load_dwordx4 v[50:53], v[24:25], off offset:-4096
	global_load_dwordx4 v[54:57], v[24:25], off offset:-2032
	global_load_dwordx4 v[58:61], v[24:25], off offset:-2048
	global_load_dwordx4 v[4:7], v[24:25], off offset:16
	global_load_dwordx4 v[62:65], v[24:25], off
	global_load_dwordx4 v[0:3], v[24:25], off offset:2064
	global_load_dwordx4 v[66:69], v[24:25], off offset:2048
	global_load_dwordx4 v[70:73], v[12:13], off offset:16
	global_load_dwordx4 v[74:77], v[12:13], off
	global_load_dwordx4 v[78:81], v[12:13], off offset:2064
	global_load_dwordx4 v[82:85], v[12:13], off offset:2048
	global_load_dwordx4 v[86:89], v[16:17], off offset:16
	global_load_dwordx4 v[90:93], v[16:17], off
	global_load_dwordx4 v[94:97], v[18:19], off offset:16
	global_load_dwordx4 v[98:101], v[18:19], off
	s_waitcnt vmcnt(18)
	v_lshlrev_b32_e32 v114, 16, v34
	v_and_b32_e32 v115, 0xffff0000, v34
	v_pk_mul_f32 v[126:127], v[114:115], v[114:115]
	v_lshlrev_b32_e32 v34, 16, v35
	v_and_b32_e32 v35, 0xffff0000, v35
	v_pk_mul_f32 v[130:131], v[34:35], v[34:35]
	v_lshlrev_b32_e32 v116, 16, v36
	v_and_b32_e32 v117, 0xffff0000, v36
	v_pk_mul_f32 v[132:133], v[116:117], v[116:117]
	v_lshlrev_b32_e32 v36, 16, v37
	v_and_b32_e32 v37, 0xffff0000, v37
	v_pk_mul_f32 v[134:135], v[36:37], v[36:37]
	v_lshlrev_b32_e32 v102, 16, v8
	v_and_b32_e32 v103, 0xffff0000, v8
	v_lshlrev_b32_e32 v8, 16, v9
	v_and_b32_e32 v9, 0xffff0000, v9
	v_pk_mul_f32 v[106:107], v[102:103], v[102:103]
	v_pk_mul_f32 v[108:109], v[8:9], v[8:9]
	v_add_f32_e32 v106, v106, v107
	v_lshlrev_b32_e32 v104, 16, v10
	v_and_b32_e32 v105, 0xffff0000, v10
	v_add_f32_e32 v106, v108, v106
	v_pk_mul_f32 v[110:111], v[104:105], v[104:105]
	v_add_f32_e32 v106, v109, v106
	v_lshlrev_b32_e32 v10, 16, v11
	v_and_b32_e32 v11, 0xffff0000, v11
	v_add_f32_e32 v106, v110, v106
	v_pk_mul_f32 v[112:113], v[10:11], v[10:11]
	v_add_f32_e32 v106, v111, v106
	v_add_f32_e32 v106, v112, v106
	v_add_f32_e32 v106, v113, v106
	v_add_f32_e32 v106, v126, v106
	v_add_f32_e32 v106, v127, v106
	v_add_f32_e32 v106, v130, v106
	v_add_f32_e32 v106, v131, v106
	v_add_f32_e32 v106, v132, v106
	v_add_f32_e32 v106, v133, v106
	s_waitcnt vmcnt(17)
	v_lshlrev_b32_e32 v118, 16, v38
	v_and_b32_e32 v119, 0xffff0000, v38
	v_add_f32_e32 v106, v134, v106
	v_pk_mul_f32 v[136:137], v[118:119], v[118:119]
	v_add_f32_e32 v106, v135, v106
	v_lshlrev_b32_e32 v38, 16, v39
	v_and_b32_e32 v39, 0xffff0000, v39
	v_add_f32_e32 v106, v136, v106
	v_pk_mul_f32 v[138:139], v[38:39], v[38:39]
	v_add_f32_e32 v106, v137, v106
	v_lshlrev_b32_e32 v120, 16, v40
	v_and_b32_e32 v121, 0xffff0000, v40
	v_add_f32_e32 v106, v138, v106
	v_pk_mul_f32 v[140:141], v[120:121], v[120:121]
	v_add_f32_e32 v106, v139, v106
	v_lshlrev_b32_e32 v40, 16, v41
	v_and_b32_e32 v41, 0xffff0000, v41
	v_add_f32_e32 v106, v140, v106
	v_pk_mul_f32 v[142:143], v[40:41], v[40:41]
	v_add_f32_e32 v106, v141, v106
	s_waitcnt vmcnt(16)
	v_lshlrev_b32_e32 v122, 16, v42
	v_and_b32_e32 v123, 0xffff0000, v42
	v_add_f32_e32 v106, v142, v106
	v_pk_mul_f32 v[144:145], v[122:123], v[122:123]
	v_add_f32_e32 v106, v143, v106
	v_lshlrev_b32_e32 v42, 16, v43
	v_and_b32_e32 v43, 0xffff0000, v43
	v_add_f32_e32 v106, v144, v106
	v_pk_mul_f32 v[146:147], v[42:43], v[42:43]
	v_add_f32_e32 v106, v145, v106
	v_lshlrev_b32_e32 v124, 16, v44
	v_and_b32_e32 v125, 0xffff0000, v44
	v_add_f32_e32 v106, v146, v106
	v_pk_mul_f32 v[148:149], v[124:125], v[124:125]
	v_add_f32_e32 v106, v147, v106
	v_lshlrev_b32_e32 v44, 16, v45
	v_and_b32_e32 v45, 0xffff0000, v45
	v_add_f32_e32 v106, v148, v106
	v_pk_mul_f32 v[150:151], v[44:45], v[44:45]
	v_add_f32_e32 v106, v149, v106
	v_add_f32_e32 v106, v150, v106
	v_add_f32_e32 v106, v151, v106
	s_nop 1
	v_add_f32_dpp v106, v106, v106 quad_perm:[1,0,3,2] row_mask:0xf bank_mask:0xf
	s_nop 1
	v_add_f32_dpp v106, v106, v106 quad_perm:[2,3,0,1] row_mask:0xf bank_mask:0xf
	s_nop 1
	v_add_f32_dpp v106, v106, v106 row_half_mirror row_mask:0xf bank_mask:0xf
	s_nop 1
	v_add_f32_dpp v106, v106, v106 row_mirror row_mask:0xf bank_mask:0xf
	ds_bpermute_b32 v107, v32, v106
	s_waitcnt lgkmcnt(0)
	v_add_f32_e32 v106, v106, v107
	ds_bpermute_b32 v107, v33, v106
	s_waitcnt lgkmcnt(0)
	v_add_f32_e32 v106, v106, v107
	v_fmamk_f32 v106, v106, 0x3a000000, v209
	v_mul_f32_e32 v107, 0x4b800000, v106
	v_cmp_gt_f32_e32 vcc, s15, v106
	s_nop 1
	v_cndmask_b32_e32 v106, v106, v107, vcc
	v_rsq_f32_e32 v106, v106
	s_nop 0
	v_mul_f32_e32 v107, 0x45800000, v106
	v_cndmask_b32_e32 v106, v106, v107, vcc
	v_pk_mul_f32 v[102:103], v[106:107], v[102:103] op_sel_hi:[0,1]
	v_pk_mul_f32 v[8:9], v[106:107], v[8:9] op_sel_hi:[0,1]
	v_pk_mul_f32 v[104:105], v[106:107], v[104:105] op_sel_hi:[0,1]
	v_pk_mul_f32 v[110:111], v[106:107], v[34:35] op_sel_hi:[0,1]
	v_pk_mul_f32 v[112:113], v[106:107], v[116:117] op_sel_hi:[0,1]
	s_waitcnt vmcnt(6)
; template <bool HAS_M, bool WRITE_X, bool WRITE_HN>
; __device__ __forceinline__ void seam_rows(const float* xin, const bf16_t* mb, const float* gpost, const float* gpre, float* xout, bf16_t* hn, int gw, int NGW, int lane) {
;     ...
;                 for (int i = 0; i < 8; ++i) v[s * 8 + i] += mv[s * 8 + i] * r1 * g[i]; }
;         }
;         if (WRITE_X) {
; #pragma unroll
;             for (int s = 0; s < 4; ++s) { *(f32x4*)(xout + ro + s * 512) = (f32x4){v[s * 8], v[s * 8 + 1], v[s * 8 + 2], v[s * 8 + 3]}; *(f32x4*)(xout + ro + s * 512 + 4) = (f32x4){v[s * 8 + 4], v[s * 8 + 5], v[s * 8 + 6], v[s * 8 + 7]}; }
;         }
;         if (WRITE_HN) {
;             float ss = 0.f;
; #pragma unroll
;             for (int i = 0; i < 32; ++i) ss += v[i] * v[i];
	v_pk_fma_f32 v[34:35], v[74:75], v[102:103], v[50:51]
	v_pk_mul_f32 v[10:11], v[106:107], v[10:11] op_sel_hi:[0,1]
	v_pk_mul_f32 v[108:109], v[106:107], v[114:115] op_sel_hi:[0,1]
	v_pk_mul_f32 v[114:115], v[106:107], v[36:37] op_sel_hi:[0,1]
	v_pk_mul_f32 v[116:117], v[106:107], v[118:119] op_sel_hi:[0,1]
	v_pk_mul_f32 v[118:119], v[106:107], v[38:39] op_sel_hi:[0,1]
	v_pk_mul_f32 v[120:121], v[106:107], v[120:121] op_sel_hi:[0,1]
	v_pk_mul_f32 v[126:127], v[106:107], v[40:41] op_sel_hi:[0,1]
	v_pk_mul_f32 v[122:123], v[106:107], v[122:123] op_sel_hi:[0,1]
	v_pk_mul_f32 v[130:131], v[106:107], v[42:43] op_sel_hi:[0,1]
	v_pk_mul_f32 v[124:125], v[106:107], v[124:125] op_sel_hi:[0,1]
	v_pk_mul_f32 v[106:107], v[106:107], v[44:45] op_sel_hi:[0,1]
	v_pk_fma_f32 v[36:37], v[76:77], v[8:9], v[52:53]
	v_pk_fma_f32 v[38:39], v[70:71], v[104:105], v[46:47]
	s_waitcnt vmcnt(5)
	v_pk_fma_f32 v[46:47], v[78:79], v[112:113], v[54:55]
	v_pk_mul_f32 v[54:55], v[34:35], v[34:35]
	v_pk_fma_f32 v[40:41], v[72:73], v[10:11], v[48:49]
	s_waitcnt vmcnt(4)
	v_pk_fma_f32 v[42:43], v[82:83], v[108:109], v[58:59]
	v_pk_fma_f32 v[44:45], v[84:85], v[110:111], v[60:61]
	v_pk_fma_f32 v[48:49], v[80:81], v[114:115], v[56:57]
	s_waitcnt vmcnt(2)
	v_pk_fma_f32 v[50:51], v[90:91], v[116:117], v[62:63]
	v_pk_fma_f32 v[52:53], v[92:93], v[118:119], v[64:65]
	v_pk_fma_f32 v[8:9], v[86:87], v[120:121], v[4:5]
	v_pk_fma_f32 v[10:11], v[88:89], v[126:127], v[6:7]
	s_waitcnt vmcnt(0)
	v_pk_fma_f32 v[4:5], v[98:99], v[122:123], v[66:67]
	v_pk_fma_f32 v[6:7], v[100:101], v[130:131], v[68:69]
	v_pk_fma_f32 v[0:1], v[94:95], v[124:125], v[0:1]
	v_pk_fma_f32 v[2:3], v[96:97], v[106:107], v[2:3]
	global_store_dwordx4 v[24:25], v[34:37], off offset:-4096
	global_store_dwordx4 v[24:25], v[38:41], off offset:-4080
	global_store_dwordx4 v[24:25], v[42:45], off offset:-2048
	global_store_dwordx4 v[24:25], v[46:49], off offset:-2032
	global_store_dwordx4 v[24:25], v[50:53], off
	global_store_dwordx4 v[24:25], v[8:11], off offset:16
	global_store_dwordx4 v[24:25], v[4:7], off offset:2048
	global_store_dwordx4 v[24:25], v[0:3], off offset:2064
	v_pk_mul_f32 v[62:63], v[36:37], v[36:37]
	v_add_f32_e32 v54, v54, v55
	v_add_f32_e32 v62, v62, v54
	v_pk_mul_f32 v[64:65], v[38:39], v[38:39]
	v_add_f32_e32 v62, v63, v62
	v_add_f32_e32 v62, v64, v62
	v_pk_mul_f32 v[66:67], v[40:41], v[40:41]
	v_add_f32_e32 v62, v65, v62
	v_add_f32_e32 v62, v66, v62
	v_pk_mul_f32 v[68:69], v[42:43], v[42:43]
	v_add_f32_e32 v62, v67, v62
	v_add_f32_e32 v62, v68, v62
	v_pk_mul_f32 v[70:71], v[44:45], v[44:45]
	v_add_f32_e32 v62, v69, v62
	v_add_f32_e32 v62, v70, v62
	v_pk_mul_f32 v[72:73], v[46:47], v[46:47]
	v_add_f32_e32 v62, v71, v62
	v_add_f32_e32 v62, v72, v62
	v_pk_mul_f32 v[74:75], v[48:49], v[48:49]
	v_add_f32_e32 v62, v73, v62
	v_add_f32_e32 v62, v74, v62
	v_pk_mul_f32 v[76:77], v[50:51], v[50:51]
	v_add_f32_e32 v62, v75, v62
	v_add_f32_e32 v62, v76, v62
	v_pk_mul_f32 v[78:79], v[52:53], v[52:53]
	v_add_f32_e32 v62, v77, v62
	v_add_f32_e32 v62, v78, v62
	v_pk_mul_f32 v[80:81], v[8:9], v[8:9]
	v_add_f32_e32 v62, v79, v62
	v_add_f32_e32 v62, v80, v62
	v_pk_mul_f32 v[82:83], v[10:11], v[10:11]
	v_add_f32_e32 v62, v81, v62
	v_add_f32_e32 v62, v82, v62
	v_pk_mul_f32 v[84:85], v[4:5], v[4:5]
	v_add_f32_e32 v62, v83, v62
	v_add_f32_e32 v62, v84, v62
	v_pk_mul_f32 v[86:87], v[6:7], v[6:7]
	v_add_f32_e32 v62, v85, v62
	v_add_f32_e32 v62, v86, v62
	v_pk_mul_f32 v[88:89], v[0:1], v[0:1]
	v_add_f32_e32 v62, v87, v62
	v_add_f32_e32 v62, v88, v62
	v_pk_mul_f32 v[90:91], v[2:3], v[2:3]
	v_add_f32_e32 v62, v89, v62
	v_add_f32_e32 v62, v90, v62
	v_add_f32_e32 v62, v91, v62
	s_nop 1
	v_lshl_add_u64 v[24:25], v[24:25], 0, s[18:19]
	v_add_f32_dpp v62, v62, v62 quad_perm:[1,0,3,2] row_mask:0xf bank_mask:0xf
	s_nop 1
	v_add_f32_dpp v62, v62, v62 quad_perm:[2,3,0,1] row_mask:0xf bank_mask:0xf
	s_nop 1
	v_add_f32_dpp v62, v62, v62 row_half_mirror row_mask:0xf bank_mask:0xf
	s_nop 1
	v_add_f32_dpp v62, v62, v62 row_mirror row_mask:0xf bank_mask:0xf
	ds_bpermute_b32 v63, v32, v62
	s_waitcnt lgkmcnt(0)
; __device__ __forceinline__ u32x4 pack8(const float* f) { u32x4 w; w.x = pk2(f[0], f[1]); w.y = pk2(f[2], f[3]); w.z = pk2(f[4], f[5]); w.w = pk2(f[6], f[7]); return w; }
; template <bool HAS_M, bool WRITE_X, bool WRITE_HN>
; __device__ __forceinline__ void seam_rows(const float* xin, const bf16_t* mb, const float* gpost, const float* gpre, float* xout, bf16_t* hn, int gw, int NGW, int lane) {
;     ...
;             for (int i = 0; i < 32; ++i) ss += v[i] * v[i];
;             const float r2 = rsqrtf(wave_sum(ss) * (1.f / 2048.f) + 1e-6f);
; #pragma unroll
;             for (int s = 0; s < 4; ++s) { float g[8], o[8]; ld8f(gpre + s * 512 + lane * 8, g);
; #pragma unroll
;                 for (int i = 0; i < 8; ++i) o[i] = v[s * 8 + i] * r2 * g[i];
;                 *(u32x4*)(hn + ro + s * 512) = pack8(o); }
	v_add_f32_e32 v62, v62, v63
	ds_bpermute_b32 v63, v33, v62
	s_waitcnt lgkmcnt(0)
	v_add_f32_e32 v62, v62, v63
	v_fmamk_f32 v62, v62, 0x3a000000, v209
	v_mul_f32_e32 v63, 0x4b800000, v62
	v_cmp_gt_f32_e32 vcc, s15, v62
	s_nop 1
	v_cndmask_b32_e32 v62, v62, v63, vcc
	v_rsq_f32_e32 v62, v62
	s_nop 0
	v_mul_f32_e32 v63, 0x45800000, v62
	v_cndmask_b32_e32 v62, v62, v63, vcc
	v_mul_f32_e32 v34, v34, v62
	v_mul_f32_e32 v35, v35, v62
	v_mul_f32_e32 v36, v36, v62
	v_mul_f32_e32 v37, v37, v62
	s_nop 0
	v_mul_f32_e32 v34, v156, v34
	v_mul_f32_e32 v35, v157, v35
	v_mul_f32_e32 v36, v158, v36
	v_mul_f32_e32 v37, v159, v37
	v_mul_f32_e32 v38, v38, v62
	v_mul_f32_e32 v39, v39, v62
	v_mul_f32_e32 v40, v40, v62
	v_mul_f32_e32 v41, v41, v62
	v_mul_f32_e32 v38, v152, v38
	v_mul_f32_e32 v39, v153, v39
	v_mul_f32_e32 v40, v154, v40
	v_mul_f32_e32 v41, v155, v41
	v_cvt_pk_bf16_f32 v34, v34, v35
	v_cvt_pk_bf16_f32 v35, v36, v37
	v_cvt_pk_bf16_f32 v36, v38, v39
	v_cvt_pk_bf16_f32 v37, v40, v41
	global_store_dwordx4 v[26:27], v[34:37], off
	s_nop 0
	v_mul_f32_e32 v42, v42, v62
	v_mul_f32_e32 v43, v43, v62
	v_mul_f32_e32 v44, v44, v62
	v_mul_f32_e32 v45, v45, v62
	v_mul_f32_e32 v46, v46, v62
	v_mul_f32_e32 v47, v47, v62
	v_mul_f32_e32 v48, v48, v62
	v_mul_f32_e32 v49, v49, v62
	v_mul_f32_e32 v11, v11, v62
	v_mul_f32_e32 v8, v8, v62
	v_mul_f32_e32 v9, v9, v62
	v_mul_f32_e32 v10, v10, v62
	v_mul_f32_e32 v3, v3, v62
	v_mul_f32_e32 v4, v4, v62
	v_mul_f32_e32 v5, v5, v62
	v_mul_f32_e32 v6, v6, v62
	v_mul_f32_e32 v7, v7, v62
	v_mul_f32_e32 v0, v0, v62
	v_mul_f32_e32 v1, v1, v62
	v_mul_f32_e32 v2, v2, v62
	s_nop 0
	v_mul_f32_e32 v34, v160, v42
	v_mul_f32_e32 v35, v161, v43
	v_mul_f32_e32 v36, v162, v44
	v_mul_f32_e32 v37, v163, v45
	s_nop 0
	v_mul_f32_e32 v38, v164, v46
	v_mul_f32_e32 v39, v165, v47
	v_mul_f32_e32 v40, v166, v48
	v_mul_f32_e32 v41, v167, v49
	v_cvt_pk_bf16_f32 v34, v34, v35
	v_cvt_pk_bf16_f32 v35, v36, v37
	v_cvt_pk_bf16_f32 v36, v38, v39
	v_cvt_pk_bf16_f32 v37, v40, v41
	global_store_dwordx4 v[26:27], v[34:37], off offset:1024
	s_nop 0
	v_mul_f32_e32 v42, v50, v62
	v_mul_f32_e32 v43, v51, v62
	v_mul_f32_e32 v44, v52, v62
	v_mul_f32_e32 v45, v53, v62
	s_nop 0
	v_mul_f32_e32 v34, v168, v42
	s_nop 0
	v_mul_f32_e32 v11, v175, v11
	v_mul_f32_e32 v35, v169, v43
	v_mul_f32_e32 v36, v170, v44
	v_mul_f32_e32 v37, v171, v45
	v_mul_f32_e32 v38, v172, v8
	v_mul_f32_e32 v39, v173, v9
	v_mul_f32_e32 v40, v174, v10
	v_cvt_pk_bf16_f32 v8, v34, v35
	v_cvt_pk_bf16_f32 v9, v36, v37
	v_cvt_pk_bf16_f32 v10, v38, v39
	v_cvt_pk_bf16_f32 v11, v40, v11
	global_store_dwordx4 v[26:27], v[8:11], off offset:2048
	s_nop 0
	s_nop 0
	v_mul_f32_e32 v4, v176, v4
	s_nop 0
	v_mul_f32_e32 v3, v183, v3
	v_mul_f32_e32 v5, v177, v5
	v_mul_f32_e32 v6, v178, v6
	v_mul_f32_e32 v7, v179, v7
	v_mul_f32_e32 v8, v180, v0
	v_mul_f32_e32 v9, v181, v1
	v_mul_f32_e32 v10, v182, v2
	v_cvt_pk_bf16_f32 v0, v4, v5
	v_cvt_pk_bf16_f32 v1, v6, v7
	v_cvt_pk_bf16_f32 v2, v8, v9
	v_cvt_pk_bf16_f32 v3, v10, v3
	global_store_dwordx4 v[26:27], v[0:3], off offset:3072
	v_lshl_add_u64 v[26:27], v[26:27], 0, s[30:31]
	s_cbranch_scc0 .LBB0_80

; template <bool HAS_M, bool WRITE_X, bool WRITE_HN>
; __device__ __forceinline__ void seam_rows(const float* xin, const bf16_t* mb, const float* gpost, const float* gpre, float* xout, bf16_t* hn, int gw, int NGW, int lane) {
;     for (int row = gw; row < M; row += NGW) {
;         const size_t ro = (size_t)row * DM + lane * 8;
;         float v[32];
; #pragma unroll
;         for (int s = 0; s < 4; ++s) ld8f(xin + ro + s * 512, v + s * 8);
;         if (HAS_M) {
;             float mv[32]; float ss = 0.f;
; #pragma unroll
;             for (int s = 0; s < 4; ++s) unpack8(*(const u32x4*)(mb + ro + s * 512), mv + s * 8);
; #pragma unroll
;             for (int i = 0; i < 32; ++i) ss += mv[i] * mv[i];
;             const float r1 = rsqrtf(wave_sum(ss) * (1.f / 2048.f) + 1e-6f);
; #pragma unroll
;             for (int s = 0; s < 4; ++s) { float g[8]; ld8f(gpost + s * 512 + lane * 8, g);
; #pragma unroll
;                 for (int i = 0; i < 8; ++i) v[s * 8 + i] += mv[s * 8 + i] * r1 * g[i]; }
.LBB0_416:
	v_add_co_u32_e32 v0, vcc, 0xefa00000, v26
	s_add_i32 s10, s10, s16
	s_nop 0
	v_addc_co_u32_e32 v1, vcc, -1, v27, vcc
	global_load_dwordx4 v[8:11], v[0:1], off
	v_add_co_u32_e32 v0, vcc, 0xefa01000, v26
	s_cmpk_gt_i32 s10, 0x3fff
	s_nop 0
	v_addc_co_u32_e32 v1, vcc, -1, v27, vcc
	global_load_dwordx4 v[34:37], v[0:1], off offset:-3072
	global_load_dwordx4 v[38:41], v[0:1], off offset:-2048
	global_load_dwordx4 v[42:45], v[0:1], off offset:-1024
	global_load_dwordx4 v[46:49], v[24:25], off offset:-4080
	global_load_dwordx4 v[50:53], v[24:25], off offset:-4096
	global_load_dwordx4 v[54:57], v[24:25], off offset:-2032
	global_load_dwordx4 v[58:61], v[24:25], off offset:-2048
	global_load_dwordx4 v[4:7], v[24:25], off offset:16
	global_load_dwordx4 v[62:65], v[24:25], off
	global_load_dwordx4 v[0:3], v[24:25], off offset:2064
	global_load_dwordx4 v[66:69], v[24:25], off offset:2048
	global_load_dwordx4 v[70:73], v[12:13], off offset:16
	global_load_dwordx4 v[74:77], v[12:13], off
	global_load_dwordx4 v[78:81], v[12:13], off offset:2064
	global_load_dwordx4 v[82:85], v[12:13], off offset:2048
	global_load_dwordx4 v[86:89], v[16:17], off offset:16
	global_load_dwordx4 v[90:93], v[16:17], off
	global_load_dwordx4 v[94:97], v[18:19], off offset:16
	global_load_dwordx4 v[98:101], v[18:19], off
	s_waitcnt vmcnt(18)
	v_lshlrev_b32_e32 v114, 16, v34
	v_and_b32_e32 v115, 0xffff0000, v34
	v_pk_mul_f32 v[126:127], v[114:115], v[114:115]
	v_lshlrev_b32_e32 v34, 16, v35
	v_and_b32_e32 v35, 0xffff0000, v35
	v_pk_mul_f32 v[130:131], v[34:35], v[34:35]
	v_lshlrev_b32_e32 v116, 16, v36
	v_and_b32_e32 v117, 0xffff0000, v36
	v_pk_mul_f32 v[132:133], v[116:117], v[116:117]
	v_lshlrev_b32_e32 v36, 16, v37
	v_and_b32_e32 v37, 0xffff0000, v37
	v_pk_mul_f32 v[134:135], v[36:37], v[36:37]
	v_lshlrev_b32_e32 v102, 16, v8
	v_and_b32_e32 v103, 0xffff0000, v8
	v_lshlrev_b32_e32 v8, 16, v9
	v_and_b32_e32 v9, 0xffff0000, v9
	v_pk_mul_f32 v[106:107], v[102:103], v[102:103]
	v_pk_mul_f32 v[108:109], v[8:9], v[8:9]
	v_add_f32_e32 v106, v106, v107
	v_lshlrev_b32_e32 v104, 16, v10
	v_and_b32_e32 v105, 0xffff0000, v10
	v_add_f32_e32 v106, v108, v106
	v_pk_mul_f32 v[110:111], v[104:105], v[104:105]
	v_add_f32_e32 v106, v109, v106
	v_lshlrev_b32_e32 v10, 16, v11
	v_and_b32_e32 v11, 0xffff0000, v11
	v_add_f32_e32 v106, v110, v106
	v_pk_mul_f32 v[112:113], v[10:11], v[10:11]
	v_add_f32_e32 v106, v111, v106
	v_add_f32_e32 v106, v112, v106
	v_add_f32_e32 v106, v113, v106
	v_add_f32_e32 v106, v126, v106
	v_add_f32_e32 v106, v127, v106
	v_add_f32_e32 v106, v130, v106
	v_add_f32_e32 v106, v131, v106
	v_add_f32_e32 v106, v132, v106
	v_add_f32_e32 v106, v133, v106
	s_waitcnt vmcnt(17)
	v_lshlrev_b32_e32 v118, 16, v38
	v_and_b32_e32 v119, 0xffff0000, v38
	v_add_f32_e32 v106, v134, v106
	v_pk_mul_f32 v[136:137], v[118:119], v[118:119]
	v_add_f32_e32 v106, v135, v106
	v_lshlrev_b32_e32 v38, 16, v39
	v_and_b32_e32 v39, 0xffff0000, v39
	v_add_f32_e32 v106, v136, v106
	v_pk_mul_f32 v[138:139], v[38:39], v[38:39]
	v_add_f32_e32 v106, v137, v106
	v_lshlrev_b32_e32 v120, 16, v40
	v_and_b32_e32 v121, 0xffff0000, v40
	v_add_f32_e32 v106, v138, v106
	v_pk_mul_f32 v[140:141], v[120:121], v[120:121]
	v_add_f32_e32 v106, v139, v106
	v_lshlrev_b32_e32 v40, 16, v41
	v_and_b32_e32 v41, 0xffff0000, v41
	v_add_f32_e32 v106, v140, v106
	v_pk_mul_f32 v[142:143], v[40:41], v[40:41]
	v_add_f32_e32 v106, v141, v106
	s_waitcnt vmcnt(16)
	v_lshlrev_b32_e32 v122, 16, v42
	v_and_b32_e32 v123, 0xffff0000, v42
	v_add_f32_e32 v106, v142, v106
	v_pk_mul_f32 v[144:145], v[122:123], v[122:123]
	v_add_f32_e32 v106, v143, v106
	v_lshlrev_b32_e32 v42, 16, v43
	v_and_b32_e32 v43, 0xffff0000, v43
	v_add_f32_e32 v106, v144, v106
	v_pk_mul_f32 v[146:147], v[42:43], v[42:43]
	v_add_f32_e32 v106, v145, v106
	v_lshlrev_b32_e32 v124, 16, v44
	v_and_b32_e32 v125, 0xffff0000, v44
	v_add_f32_e32 v106, v146, v106
	v_pk_mul_f32 v[148:149], v[124:125], v[124:125]
	v_add_f32_e32 v106, v147, v106
	v_lshlrev_b32_e32 v44, 16, v45
	v_and_b32_e32 v45, 0xffff0000, v45
	v_add_f32_e32 v106, v148, v106
	v_pk_mul_f32 v[150:151], v[44:45], v[44:45]
	v_add_f32_e32 v106, v149, v106
	v_add_f32_e32 v106, v150, v106
	v_add_f32_e32 v106, v151, v106
	s_nop 1
	v_add_f32_dpp v106, v106, v106 quad_perm:[1,0,3,2] row_mask:0xf bank_mask:0xf
	s_nop 1
	v_add_f32_dpp v106, v106, v106 quad_perm:[2,3,0,1] row_mask:0xf bank_mask:0xf
	s_nop 1
	v_add_f32_dpp v106, v106, v106 row_half_mirror row_mask:0xf bank_mask:0xf
	s_nop 1
	v_add_f32_dpp v106, v106, v106 row_mirror row_mask:0xf bank_mask:0xf
	ds_bpermute_b32 v107, v32, v106
	s_waitcnt lgkmcnt(0)
	v_add_f32_e32 v106, v106, v107
	ds_bpermute_b32 v107, v33, v106
	s_waitcnt lgkmcnt(0)
	v_add_f32_e32 v106, v106, v107
	v_fmamk_f32 v106, v106, 0x3a000000, v209
	v_mul_f32_e32 v107, 0x4b800000, v106
	v_cmp_gt_f32_e32 vcc, s15, v106
	s_nop 1
	v_cndmask_b32_e32 v106, v106, v107, vcc
	v_rsq_f32_e32 v106, v106
	s_nop 0
	v_mul_f32_e32 v107, 0x45800000, v106
	v_cndmask_b32_e32 v106, v106, v107, vcc
	v_pk_mul_f32 v[102:103], v[106:107], v[102:103] op_sel_hi:[0,1]
	v_pk_mul_f32 v[8:9], v[106:107], v[8:9] op_sel_hi:[0,1]
	v_pk_mul_f32 v[104:105], v[106:107], v[104:105] op_sel_hi:[0,1]
	v_pk_mul_f32 v[110:111], v[106:107], v[34:35] op_sel_hi:[0,1]
	v_pk_mul_f32 v[112:113], v[106:107], v[116:117] op_sel_hi:[0,1]
	s_waitcnt vmcnt(6)
; template <bool HAS_M, bool WRITE_X, bool WRITE_HN>
; __device__ __forceinline__ void seam_rows(const float* xin, const bf16_t* mb, const float* gpost, const float* gpre, float* xout, bf16_t* hn, int gw, int NGW, int lane) {
;     ...
;                 for (int i = 0; i < 8; ++i) v[s * 8 + i] += mv[s * 8 + i] * r1 * g[i]; }
;         }
;         if (WRITE_X) {
; #pragma unroll
;             for (int s = 0; s < 4; ++s) { *(f32x4*)(xout + ro + s * 512) = (f32x4){v[s * 8], v[s * 8 + 1], v[s * 8 + 2], v[s * 8 + 3]}; *(f32x4*)(xout + ro + s * 512 + 4) = (f32x4){v[s * 8 + 4], v[s * 8 + 5], v[s * 8 + 6], v[s * 8 + 7]}; }
;         }
;         if (WRITE_HN) {
;             float ss = 0.f;
; #pragma unroll
;             for (int i = 0; i < 32; ++i) ss += v[i] * v[i];
	v_pk_fma_f32 v[34:35], v[74:75], v[102:103], v[50:51]
	v_pk_mul_f32 v[10:11], v[106:107], v[10:11] op_sel_hi:[0,1]
	v_pk_mul_f32 v[108:109], v[106:107], v[114:115] op_sel_hi:[0,1]
	v_pk_mul_f32 v[114:115], v[106:107], v[36:37] op_sel_hi:[0,1]
	v_pk_mul_f32 v[116:117], v[106:107], v[118:119] op_sel_hi:[0,1]
	v_pk_mul_f32 v[118:119], v[106:107], v[38:39] op_sel_hi:[0,1]
	v_pk_mul_f32 v[120:121], v[106:107], v[120:121] op_sel_hi:[0,1]
	v_pk_mul_f32 v[126:127], v[106:107], v[40:41] op_sel_hi:[0,1]
	v_pk_mul_f32 v[122:123], v[106:107], v[122:123] op_sel_hi:[0,1]
	v_pk_mul_f32 v[130:131], v[106:107], v[42:43] op_sel_hi:[0,1]
	v_pk_mul_f32 v[124:125], v[106:107], v[124:125] op_sel_hi:[0,1]
	v_pk_mul_f32 v[106:107], v[106:107], v[44:45] op_sel_hi:[0,1]
	v_pk_fma_f32 v[36:37], v[76:77], v[8:9], v[52:53]
	v_pk_fma_f32 v[38:39], v[70:71], v[104:105], v[46:47]
	s_waitcnt vmcnt(5)
	v_pk_fma_f32 v[46:47], v[78:79], v[112:113], v[54:55]
	v_pk_mul_f32 v[54:55], v[34:35], v[34:35]
	v_pk_fma_f32 v[40:41], v[72:73], v[10:11], v[48:49]
	s_waitcnt vmcnt(4)
	v_pk_fma_f32 v[42:43], v[82:83], v[108:109], v[58:59]
	v_pk_fma_f32 v[44:45], v[84:85], v[110:111], v[60:61]
	v_pk_fma_f32 v[48:49], v[80:81], v[114:115], v[56:57]
	s_waitcnt vmcnt(2)
	v_pk_fma_f32 v[50:51], v[90:91], v[116:117], v[62:63]
	v_pk_fma_f32 v[52:53], v[92:93], v[118:119], v[64:65]
	v_pk_fma_f32 v[8:9], v[86:87], v[120:121], v[4:5]
	v_pk_fma_f32 v[10:11], v[88:89], v[126:127], v[6:7]
	s_waitcnt vmcnt(0)
	v_pk_fma_f32 v[4:5], v[98:99], v[122:123], v[66:67]
	v_pk_fma_f32 v[6:7], v[100:101], v[130:131], v[68:69]
	v_pk_fma_f32 v[0:1], v[94:95], v[124:125], v[0:1]
	v_pk_fma_f32 v[2:3], v[96:97], v[106:107], v[2:3]
	global_store_dwordx4 v[24:25], v[34:37], off offset:-4096
	global_store_dwordx4 v[24:25], v[38:41], off offset:-4080
	global_store_dwordx4 v[24:25], v[42:45], off offset:-2048
	global_store_dwordx4 v[24:25], v[46:49], off offset:-2032
	global_store_dwordx4 v[24:25], v[50:53], off
	global_store_dwordx4 v[24:25], v[8:11], off offset:16
	global_store_dwordx4 v[24:25], v[4:7], off offset:2048
	global_store_dwordx4 v[24:25], v[0:3], off offset:2064
	v_pk_mul_f32 v[62:63], v[36:37], v[36:37]
	v_add_f32_e32 v54, v54, v55
	v_add_f32_e32 v62, v62, v54
	v_pk_mul_f32 v[64:65], v[38:39], v[38:39]
	v_add_f32_e32 v62, v63, v62
	v_add_f32_e32 v62, v64, v62
	v_pk_mul_f32 v[66:67], v[40:41], v[40:41]
	v_add_f32_e32 v62, v65, v62
	v_add_f32_e32 v62, v66, v62
	v_pk_mul_f32 v[68:69], v[42:43], v[42:43]
	v_add_f32_e32 v62, v67, v62
	v_add_f32_e32 v62, v68, v62
	v_pk_mul_f32 v[70:71], v[44:45], v[44:45]
	v_add_f32_e32 v62, v69, v62
	v_add_f32_e32 v62, v70, v62
	v_pk_mul_f32 v[72:73], v[46:47], v[46:47]
	v_add_f32_e32 v62, v71, v62
	v_add_f32_e32 v62, v72, v62
	v_pk_mul_f32 v[74:75], v[48:49], v[48:49]
	v_add_f32_e32 v62, v73, v62
	v_add_f32_e32 v62, v74, v62
	v_pk_mul_f32 v[76:77], v[50:51], v[50:51]
	v_add_f32_e32 v62, v75, v62
	v_add_f32_e32 v62, v76, v62
	v_pk_mul_f32 v[78:79], v[52:53], v[52:53]
	v_add_f32_e32 v62, v77, v62
	v_add_f32_e32 v62, v78, v62
	v_pk_mul_f32 v[80:81], v[8:9], v[8:9]
	v_add_f32_e32 v62, v79, v62
	v_add_f32_e32 v62, v80, v62
	v_pk_mul_f32 v[82:83], v[10:11], v[10:11]
	v_add_f32_e32 v62, v81, v62
	v_add_f32_e32 v62, v82, v62
	v_pk_mul_f32 v[84:85], v[4:5], v[4:5]
	v_add_f32_e32 v62, v83, v62
	v_add_f32_e32 v62, v84, v62
	v_pk_mul_f32 v[86:87], v[6:7], v[6:7]
	v_add_f32_e32 v62, v85, v62
	v_add_f32_e32 v62, v86, v62
	v_pk_mul_f32 v[88:89], v[0:1], v[0:1]
	v_add_f32_e32 v62, v87, v62
	v_add_f32_e32 v62, v88, v62
	v_pk_mul_f32 v[90:91], v[2:3], v[2:3]
	v_add_f32_e32 v62, v89, v62
	v_add_f32_e32 v62, v90, v62
	v_add_f32_e32 v62, v91, v62
	s_nop 1
	v_lshl_add_u64 v[24:25], v[24:25], 0, s[8:9]
	v_add_f32_dpp v62, v62, v62 quad_perm:[1,0,3,2] row_mask:0xf bank_mask:0xf
	s_nop 1
	v_add_f32_dpp v62, v62, v62 quad_perm:[2,3,0,1] row_mask:0xf bank_mask:0xf
	s_nop 1
	v_add_f32_dpp v62, v62, v62 row_half_mirror row_mask:0xf bank_mask:0xf
	s_nop 1
	v_add_f32_dpp v62, v62, v62 row_mirror row_mask:0xf bank_mask:0xf
	ds_bpermute_b32 v63, v32, v62
	s_waitcnt lgkmcnt(0)
; __device__ __forceinline__ u32x4 pack8(const float* f) { u32x4 w; w.x = pk2(f[0], f[1]); w.y = pk2(f[2], f[3]); w.z = pk2(f[4], f[5]); w.w = pk2(f[6], f[7]); return w; }
; template <bool HAS_M, bool WRITE_X, bool WRITE_HN>
; __device__ __forceinline__ void seam_rows(const float* xin, const bf16_t* mb, const float* gpost, const float* gpre, float* xout, bf16_t* hn, int gw, int NGW, int lane) {
;     ...
;             for (int i = 0; i < 32; ++i) ss += v[i] * v[i];
;             const float r2 = rsqrtf(wave_sum(ss) * (1.f / 2048.f) + 1e-6f);
; #pragma unroll
;             for (int s = 0; s < 4; ++s) { float g[8], o[8]; ld8f(gpre + s * 512 + lane * 8, g);
; #pragma unroll
;                 for (int i = 0; i < 8; ++i) o[i] = v[s * 8 + i] * r2 * g[i];
;                 *(u32x4*)(hn + ro + s * 512) = pack8(o); }
	v_add_f32_e32 v62, v62, v63
	ds_bpermute_b32 v63, v33, v62
	s_waitcnt lgkmcnt(0)
	v_add_f32_e32 v62, v62, v63
	v_fmamk_f32 v62, v62, 0x3a000000, v209
	v_mul_f32_e32 v63, 0x4b800000, v62
	v_cmp_gt_f32_e32 vcc, s15, v62
	s_nop 1
	v_cndmask_b32_e32 v62, v62, v63, vcc
	v_rsq_f32_e32 v62, v62
	s_nop 0
	v_mul_f32_e32 v63, 0x45800000, v62
	v_cndmask_b32_e32 v62, v62, v63, vcc
	v_mul_f32_e32 v34, v34, v62
	v_mul_f32_e32 v35, v35, v62
	v_mul_f32_e32 v36, v36, v62
	v_mul_f32_e32 v37, v37, v62
	s_nop 0
	v_mul_f32_e32 v34, v156, v34
	v_mul_f32_e32 v35, v157, v35
	v_mul_f32_e32 v36, v158, v36
	v_mul_f32_e32 v37, v159, v37
	v_mul_f32_e32 v38, v38, v62
	v_mul_f32_e32 v39, v39, v62
	v_mul_f32_e32 v40, v40, v62
	v_mul_f32_e32 v41, v41, v62
	v_mul_f32_e32 v38, v152, v38
	v_mul_f32_e32 v39, v153, v39
	v_mul_f32_e32 v40, v154, v40
	v_mul_f32_e32 v41, v155, v41
	v_cvt_pk_bf16_f32 v34, v34, v35
	v_cvt_pk_bf16_f32 v35, v36, v37
	v_cvt_pk_bf16_f32 v36, v38, v39
	v_cvt_pk_bf16_f32 v37, v40, v41
	global_store_dwordx4 v[26:27], v[34:37], off
	s_nop 0
	v_mul_f32_e32 v42, v42, v62
	v_mul_f32_e32 v43, v43, v62
	v_mul_f32_e32 v44, v44, v62
	v_mul_f32_e32 v45, v45, v62
	v_mul_f32_e32 v46, v46, v62
	v_mul_f32_e32 v47, v47, v62
	v_mul_f32_e32 v48, v48, v62
	v_mul_f32_e32 v49, v49, v62
	v_mul_f32_e32 v11, v11, v62
	v_mul_f32_e32 v8, v8, v62
	v_mul_f32_e32 v9, v9, v62
	v_mul_f32_e32 v10, v10, v62
	v_mul_f32_e32 v3, v3, v62
	v_mul_f32_e32 v4, v4, v62
	v_mul_f32_e32 v5, v5, v62
	v_mul_f32_e32 v6, v6, v62
	v_mul_f32_e32 v7, v7, v62
	v_mul_f32_e32 v0, v0, v62
	v_mul_f32_e32 v1, v1, v62
	v_mul_f32_e32 v2, v2, v62
	s_nop 0
	v_mul_f32_e32 v34, v160, v42
	v_mul_f32_e32 v35, v161, v43
	v_mul_f32_e32 v36, v162, v44
	v_mul_f32_e32 v37, v163, v45
	s_nop 0
	v_mul_f32_e32 v38, v164, v46
	v_mul_f32_e32 v39, v165, v47
	v_mul_f32_e32 v40, v166, v48
	v_mul_f32_e32 v41, v167, v49
	v_cvt_pk_bf16_f32 v34, v34, v35
	v_cvt_pk_bf16_f32 v35, v36, v37
	v_cvt_pk_bf16_f32 v36, v38, v39
	v_cvt_pk_bf16_f32 v37, v40, v41
	global_store_dwordx4 v[26:27], v[34:37], off offset:1024
	s_nop 0
	v_mul_f32_e32 v42, v50, v62
	v_mul_f32_e32 v43, v51, v62
	v_mul_f32_e32 v44, v52, v62
	v_mul_f32_e32 v45, v53, v62
	s_nop 0
	v_mul_f32_e32 v34, v168, v42
	s_nop 0
	v_mul_f32_e32 v11, v175, v11
	v_mul_f32_e32 v35, v169, v43
	v_mul_f32_e32 v36, v170, v44
	v_mul_f32_e32 v37, v171, v45
	v_mul_f32_e32 v38, v172, v8
	v_mul_f32_e32 v39, v173, v9
	v_mul_f32_e32 v40, v174, v10
	v_cvt_pk_bf16_f32 v8, v34, v35
	v_cvt_pk_bf16_f32 v9, v36, v37
	v_cvt_pk_bf16_f32 v10, v38, v39
	v_cvt_pk_bf16_f32 v11, v40, v11
	global_store_dwordx4 v[26:27], v[8:11], off offset:2048
	s_nop 0
	s_nop 0
	v_mul_f32_e32 v4, v176, v4
	s_nop 0
	v_mul_f32_e32 v3, v183, v3
	v_mul_f32_e32 v5, v177, v5
	v_mul_f32_e32 v6, v178, v6
	v_mul_f32_e32 v7, v179, v7
	v_mul_f32_e32 v8, v180, v0
	v_mul_f32_e32 v9, v181, v1
	v_mul_f32_e32 v10, v182, v2
	v_cvt_pk_bf16_f32 v0, v4, v5
	v_cvt_pk_bf16_f32 v1, v6, v7
	v_cvt_pk_bf16_f32 v2, v8, v9
	v_cvt_pk_bf16_f32 v3, v10, v3
	global_store_dwordx4 v[26:27], v[0:3], off offset:3072
	v_lshl_add_u64 v[26:27], v[26:27], 0, s[12:13]
	s_cbranch_scc0 .LBB0_416

; template <bool HAS_M, bool WRITE_X, bool WRITE_HN>
; __device__ __forceinline__ void seam_rows(const float* xin, const bf16_t* mb, const float* gpost, const float* gpre, float* xout, bf16_t* hn, int gw, int NGW, int lane) {
;     for (int row = gw; row < M; row += NGW) {
;         const size_t ro = (size_t)row * DM + lane * 8;
;         float v[32];
; #pragma unroll
;         for (int s = 0; s < 4; ++s) ld8f(xin + ro + s * 512, v + s * 8);
;         if (HAS_M) {
;             float mv[32]; float ss = 0.f;
; #pragma unroll
;             for (int s = 0; s < 4; ++s) unpack8(*(const u32x4*)(mb + ro + s * 512), mv + s * 8);
; #pragma unroll
;             for (int i = 0; i < 32; ++i) ss += mv[i] * mv[i];
;             const float r1 = rsqrtf(wave_sum(ss) * (1.f / 2048.f) + 1e-6f);
; #pragma unroll
;             for (int s = 0; s < 4; ++s) { float g[8]; ld8f(gpost + s * 512 + lane * 8, g);
; #pragma unroll
;                 for (int i = 0; i < 8; ++i) v[s * 8 + i] += mv[s * 8 + i] * r1 * g[i]; }
.LBB0_466:
	s_nop 0
	v_lshl_add_u64 v[0:1], s[8:9], 0, v[128:129]
	v_add_co_u32_e32 v4, vcc, 0x1000, v0
	global_load_dwordx4 v[20:23], v[0:1], off offset:16
	global_load_dwordx4 v[24:27], v[0:1], off
	global_load_dwordx4 v[12:15], v[0:1], off offset:2064
	global_load_dwordx4 v[16:19], v[0:1], off offset:2048
	v_lshl_add_u64 v[2:3], v[0:1], 0, s[26:27]
	v_addc_co_u32_e32 v5, vcc, 0, v1, vcc
	v_lshl_add_u64 v[0:1], v[0:1], 0, s[34:35]
	global_load_dwordx4 v[32:35], v[4:5], off
	global_load_dwordx4 v[8:11], v[2:3], off offset:16
	s_nop 0
	global_load_dwordx4 v[4:7], v[4:5], off offset:2048
	s_nop 0
	global_load_dwordx4 v[0:3], v[0:1], off offset:16
	s_nop 0
	global_load_dwordx4 v[58:61], v[52:53], off offset:-3072
	global_load_dwordx4 v[68:71], v[52:53], off offset:-2048
	global_load_dwordx4 v[72:75], v[52:53], off offset:-1024
	global_load_dwordx4 v[76:79], v[52:53], off
	global_load_dwordx4 v[36:39], v[40:41], off offset:16
	global_load_dwordx4 v[28:31], v[40:41], off
	global_load_dwordx4 v[80:83], v[40:41], off offset:2064
	global_load_dwordx4 v[84:87], v[40:41], off offset:2048
	s_movk_i32 s2, 0x1000
	s_add_i32 s7, s7, s16
	s_add_u32 s8, s8, s12
	s_addc_u32 s9, s9, s13
	s_waitcnt vmcnt(7)
	v_lshlrev_b32_e32 v54, 16, v58
	v_and_b32_e32 v55, 0xffff0000, v58
	v_pk_mul_f32 v[96:97], v[54:55], v[54:55]
	v_lshlrev_b32_e32 v56, 16, v59
	v_and_b32_e32 v57, 0xffff0000, v59
	v_pk_mul_f32 v[98:99], v[56:57], v[56:57]
	v_add_f32_e32 v96, v96, v97
	v_lshlrev_b32_e32 v58, 16, v60
	v_and_b32_e32 v59, 0xffff0000, v60
	v_add_f32_e32 v96, v98, v96
	v_pk_mul_f32 v[100:101], v[58:59], v[58:59]
	v_add_f32_e32 v96, v99, v96
	v_lshlrev_b32_e32 v60, 16, v61
	v_and_b32_e32 v61, 0xffff0000, v61
	v_add_f32_e32 v96, v100, v96
	v_pk_mul_f32 v[102:103], v[60:61], v[60:61]
	v_add_f32_e32 v96, v101, v96
	s_waitcnt vmcnt(6)
	v_lshlrev_b32_e32 v104, 16, v68
	v_and_b32_e32 v105, 0xffff0000, v68
	v_lshlrev_b32_e32 v108, 16, v69
	v_and_b32_e32 v109, 0xffff0000, v69
	v_lshlrev_b32_e32 v112, 16, v70
	v_and_b32_e32 v113, 0xffff0000, v70
	v_lshlrev_b32_e32 v116, 16, v71
	v_and_b32_e32 v117, 0xffff0000, v71
	global_load_dwordx4 v[68:71], v[44:45], off offset:16
	global_load_dwordx4 v[88:91], v[44:45], off
	v_add_f32_e32 v96, v102, v96
	v_pk_mul_f32 v[106:107], v[104:105], v[104:105]
	v_add_f32_e32 v96, v103, v96
	v_add_f32_e32 v96, v106, v96
	v_pk_mul_f32 v[110:111], v[108:109], v[108:109]
	s_waitcnt vmcnt(7)
	v_lshlrev_b32_e32 v120, 16, v72
	v_and_b32_e32 v121, 0xffff0000, v72
	v_lshlrev_b32_e32 v124, 16, v73
	v_and_b32_e32 v125, 0xffff0000, v73
	v_lshlrev_b32_e32 v130, 16, v74
	v_and_b32_e32 v131, 0xffff0000, v74
	v_lshlrev_b32_e32 v134, 16, v75
	v_and_b32_e32 v135, 0xffff0000, v75
	global_load_dwordx4 v[72:75], v[46:47], off offset:16
	global_load_dwordx4 v[92:95], v[46:47], off
	v_add_f32_e32 v96, v107, v96
	v_add_f32_e32 v96, v110, v96
	v_pk_mul_f32 v[114:115], v[112:113], v[112:113]
	v_add_f32_e32 v96, v111, v96
	v_add_f32_e32 v96, v114, v96
	v_pk_mul_f32 v[118:119], v[116:117], v[116:117]
	v_add_f32_e32 v96, v115, v96
	v_add_f32_e32 v96, v118, v96
	v_pk_mul_f32 v[122:123], v[120:121], v[120:121]
	v_add_f32_e32 v96, v119, v96
	v_add_f32_e32 v96, v122, v96
	v_pk_mul_f32 v[126:127], v[124:125], v[124:125]
	v_add_f32_e32 v96, v123, v96
	v_add_f32_e32 v96, v126, v96
	v_pk_mul_f32 v[132:133], v[130:131], v[130:131]
	v_add_f32_e32 v96, v127, v96
	v_add_f32_e32 v96, v132, v96
	v_pk_mul_f32 v[136:137], v[134:135], v[134:135]
	v_add_f32_e32 v96, v133, v96
	s_waitcnt vmcnt(8)
	v_lshlrev_b32_e32 v138, 16, v76
	v_and_b32_e32 v139, 0xffff0000, v76
	v_add_f32_e32 v96, v136, v96
	v_pk_mul_f32 v[140:141], v[138:139], v[138:139]
	v_add_f32_e32 v96, v137, v96
	v_lshlrev_b32_e32 v76, 16, v77
	v_and_b32_e32 v77, 0xffff0000, v77
	v_add_f32_e32 v96, v140, v96
	v_pk_mul_f32 v[142:143], v[76:77], v[76:77]
	v_add_f32_e32 v96, v141, v96
	v_lshlrev_b32_e32 v144, 16, v78
	v_and_b32_e32 v145, 0xffff0000, v78
	v_add_f32_e32 v96, v142, v96
	v_pk_mul_f32 v[146:147], v[144:145], v[144:145]
	v_add_f32_e32 v96, v143, v96
	v_lshlrev_b32_e32 v78, 16, v79
	v_and_b32_e32 v79, 0xffff0000, v79
	v_add_f32_e32 v96, v146, v96
	v_pk_mul_f32 v[148:149], v[78:79], v[78:79]
	v_add_f32_e32 v96, v147, v96
	v_add_f32_e32 v96, v148, v96
	v_add_f32_e32 v96, v149, v96
	s_nop 1
	v_add_f32_dpp v96, v96, v96 quad_perm:[1,0,3,2] row_mask:0xf bank_mask:0xf
	s_nop 1
	v_add_f32_dpp v96, v96, v96 quad_perm:[2,3,0,1] row_mask:0xf bank_mask:0xf
	s_nop 1
	v_add_f32_dpp v96, v96, v96 row_half_mirror row_mask:0xf bank_mask:0xf
	s_nop 1
	v_add_f32_dpp v96, v96, v96 row_mirror row_mask:0xf bank_mask:0xf
	ds_bpermute_b32 v97, v66, v96
	s_waitcnt lgkmcnt(0)
	v_add_f32_e32 v96, v96, v97
	ds_bpermute_b32 v97, v67, v96
	s_waitcnt lgkmcnt(0)
	v_add_f32_e32 v96, v96, v97
	v_fmamk_f32 v96, v96, 0x3a000000, v209
	v_cmp_gt_f32_e32 vcc, s15, v96
	v_mul_f32_e32 v97, 0x4b800000, v96
	s_nop 0
	v_cndmask_b32_e32 v96, v96, v97, vcc
	v_rsq_f32_e32 v96, v96
	s_nop 0
	v_mul_f32_e32 v97, 0x45800000, v96
	v_cndmask_b32_e32 v96, v96, v97, vcc
	v_pk_mul_f32 v[54:55], v[96:97], v[54:55] op_sel_hi:[0,1]
	s_waitcnt vmcnt(6)
	v_pk_fma_f32 v[28:29], v[28:29], v[54:55], v[24:25]
	v_pk_mul_f32 v[24:25], v[96:97], v[56:57] op_sel_hi:[0,1]
	v_pk_fma_f32 v[30:31], v[30:31], v[24:25], v[26:27]
	v_pk_mul_f32 v[24:25], v[96:97], v[58:59] op_sel_hi:[0,1]
	v_pk_fma_f32 v[24:25], v[36:37], v[24:25], v[20:21]
	v_pk_mul_f32 v[20:21], v[96:97], v[60:61] op_sel_hi:[0,1]
	v_pk_fma_f32 v[26:27], v[38:39], v[20:21], v[22:23]
	v_pk_mul_f32 v[20:21], v[96:97], v[104:105] op_sel_hi:[0,1]
	s_waitcnt vmcnt(4)
; template <bool HAS_M, bool WRITE_X, bool WRITE_HN>
; __device__ __forceinline__ void seam_rows(const float* xin, const bf16_t* mb, const float* gpost, const float* gpre, float* xout, bf16_t* hn, int gw, int NGW, int lane) {
;     ...
;                 for (int i = 0; i < 8; ++i) v[s * 8 + i] += mv[s * 8 + i] * r1 * g[i]; }
;         }
;         if (WRITE_X) {
; #pragma unroll
;             for (int s = 0; s < 4; ++s) { *(f32x4*)(xout + ro + s * 512) = (f32x4){v[s * 8], v[s * 8 + 1], v[s * 8 + 2], v[s * 8 + 3]}; *(f32x4*)(xout + ro + s * 512 + 4) = (f32x4){v[s * 8 + 4], v[s * 8 + 5], v[s * 8 + 6], v[s * 8 + 7]}; }
;         }
;         if (WRITE_HN) {
;             float ss = 0.f;
; #pragma unroll
;             for (int i = 0; i < 32; ++i) ss += v[i] * v[i];
	v_pk_fma_f32 v[20:21], v[84:85], v[20:21], v[16:17]
	v_pk_mul_f32 v[16:17], v[96:97], v[108:109] op_sel_hi:[0,1]
	v_pk_fma_f32 v[22:23], v[86:87], v[16:17], v[18:19]
	v_pk_mul_f32 v[16:17], v[96:97], v[112:113] op_sel_hi:[0,1]
	v_pk_fma_f32 v[16:17], v[80:81], v[16:17], v[12:13]
	v_pk_mul_f32 v[12:13], v[96:97], v[116:117] op_sel_hi:[0,1]
	v_pk_fma_f32 v[18:19], v[82:83], v[12:13], v[14:15]
	v_pk_mul_f32 v[12:13], v[96:97], v[120:121] op_sel_hi:[0,1]
	s_waitcnt vmcnt(2)
	v_pk_fma_f32 v[12:13], v[88:89], v[12:13], v[32:33]
	v_pk_mul_f32 v[32:33], v[96:97], v[130:131] op_sel_hi:[0,1]
	v_pk_fma_f32 v[8:9], v[68:69], v[32:33], v[8:9]
	v_pk_mul_f32 v[32:33], v[96:97], v[134:135] op_sel_hi:[0,1]
	v_pk_fma_f32 v[10:11], v[70:71], v[32:33], v[10:11]
	v_pk_mul_f32 v[32:33], v[96:97], v[138:139] op_sel_hi:[0,1]
	s_waitcnt vmcnt(0)
	v_pk_fma_f32 v[4:5], v[92:93], v[32:33], v[4:5]
	v_pk_mul_f32 v[32:33], v[96:97], v[76:77] op_sel_hi:[0,1]
	v_pk_fma_f32 v[6:7], v[94:95], v[32:33], v[6:7]
	v_pk_mul_f32 v[32:33], v[96:97], v[144:145] op_sel_hi:[0,1]
	v_pk_fma_f32 v[0:1], v[72:73], v[32:33], v[0:1]
	v_pk_mul_f32 v[32:33], v[96:97], v[78:79] op_sel_hi:[0,1]
	v_pk_fma_f32 v[2:3], v[74:75], v[32:33], v[2:3]
	v_lshl_add_u64 v[32:33], s[30:31], 0, v[128:129]
	v_pk_mul_f32 v[14:15], v[96:97], v[124:125] op_sel_hi:[0,1]
	global_store_dwordx4 v[32:33], v[28:31], off
	global_store_dwordx4 v[32:33], v[24:27], off offset:16
	global_store_dwordx4 v[32:33], v[20:23], off offset:2048
	global_store_dwordx4 v[32:33], v[16:19], off offset:2064
	v_add_co_u32_e32 v32, vcc, s2, v32
	v_pk_fma_f32 v[14:15], v[90:91], v[14:15], v[34:35]
	s_nop 0
	v_addc_co_u32_e32 v33, vcc, 0, v33, vcc
	global_store_dwordx4 v[32:33], v[12:15], off
	global_store_dwordx4 v[32:33], v[8:11], off offset:16
	global_store_dwordx4 v[32:33], v[4:7], off offset:2048
	global_store_dwordx4 v[32:33], v[0:3], off offset:2064
	v_pk_mul_f32 v[32:33], v[28:29], v[28:29]
	v_pk_mul_f32 v[34:35], v[30:31], v[30:31]
	v_add_f32_e32 v32, v32, v33
	v_add_f32_e32 v32, v34, v32
	v_pk_mul_f32 v[36:37], v[24:25], v[24:25]
	v_add_f32_e32 v32, v35, v32
	v_add_f32_e32 v32, v36, v32
	v_pk_mul_f32 v[38:39], v[26:27], v[26:27]
	v_add_f32_e32 v32, v37, v32
	v_add_f32_e32 v32, v38, v32
	v_pk_mul_f32 v[54:55], v[20:21], v[20:21]
	v_add_f32_e32 v32, v39, v32
	v_add_f32_e32 v32, v54, v32
	v_pk_mul_f32 v[56:57], v[22:23], v[22:23]
	v_add_f32_e32 v32, v55, v32
	v_add_f32_e32 v32, v56, v32
	v_add_f32_e32 v32, v57, v32
	v_pk_mul_f32 v[58:59], v[16:17], v[16:17]
	v_pk_mul_f32 v[60:61], v[18:19], v[18:19]
	v_add_f32_e32 v32, v58, v32
	v_add_f32_e32 v32, v59, v32
	v_add_f32_e32 v32, v60, v32
	v_pk_mul_f32 v[68:69], v[12:13], v[12:13]
	v_add_f32_e32 v32, v61, v32
	v_add_f32_e32 v32, v68, v32
	v_pk_mul_f32 v[70:71], v[14:15], v[14:15]
	v_add_f32_e32 v32, v69, v32
	v_add_f32_e32 v32, v70, v32
	v_pk_mul_f32 v[72:73], v[8:9], v[8:9]
	v_add_f32_e32 v32, v71, v32
	v_add_f32_e32 v32, v72, v32
	v_pk_mul_f32 v[74:75], v[10:11], v[10:11]
	v_add_f32_e32 v32, v73, v32
	v_add_f32_e32 v32, v74, v32
	v_pk_mul_f32 v[76:77], v[4:5], v[4:5]
	v_add_f32_e32 v32, v75, v32
	v_add_f32_e32 v32, v76, v32
	v_pk_mul_f32 v[78:79], v[6:7], v[6:7]
	v_add_f32_e32 v32, v77, v32
	v_add_f32_e32 v32, v78, v32
	v_pk_mul_f32 v[80:81], v[0:1], v[0:1]
	v_add_f32_e32 v32, v79, v32
	v_add_f32_e32 v32, v80, v32
	v_pk_mul_f32 v[82:83], v[2:3], v[2:3]
	v_add_f32_e32 v32, v81, v32
	v_add_f32_e32 v32, v82, v32
	v_add_f32_e32 v32, v83, v32
	ds_bpermute_b32 v33, v62, v32
	s_brev_b32 s2, 63
	s_add_u32 s30, s30, s12
	s_addc_u32 s31, s31, s13
	s_cmpk_gt_i32 s7, 0x3fff
	s_waitcnt lgkmcnt(0)
; __device__ __forceinline__ u32x4 pack8(const float* f) { u32x4 w; w.x = pk2(f[0], f[1]); w.y = pk2(f[2], f[3]); w.z = pk2(f[4], f[5]); w.w = pk2(f[6], f[7]); return w; }
; template <bool HAS_M, bool WRITE_X, bool WRITE_HN>
; __device__ __forceinline__ void seam_rows(const float* xin, const bf16_t* mb, const float* gpost, const float* gpre, float* xout, bf16_t* hn, int gw, int NGW, int lane) {
;     ...
;             for (int i = 0; i < 32; ++i) ss += v[i] * v[i];
;             const float r2 = rsqrtf(wave_sum(ss) * (1.f / 2048.f) + 1e-6f);
; #pragma unroll
;             for (int s = 0; s < 4; ++s) { float g[8], o[8]; ld8f(gpre + s * 512 + lane * 8, g);
; #pragma unroll
;                 for (int i = 0; i < 8; ++i) o[i] = v[s * 8 + i] * r2 * g[i];
;                 *(u32x4*)(hn + ro + s * 512) = pack8(o); }
	v_add_f32_e32 v32, v32, v33
	ds_bpermute_b32 v33, v63, v32
	s_waitcnt lgkmcnt(0)
	v_add_f32_e32 v32, v32, v33
	ds_bpermute_b32 v33, v64, v32
	s_waitcnt lgkmcnt(0)
	v_add_f32_e32 v32, v32, v33
	ds_bpermute_b32 v33, v65, v32
	s_waitcnt lgkmcnt(0)
	v_add_f32_e32 v32, v32, v33
	ds_bpermute_b32 v33, v66, v32
	s_waitcnt lgkmcnt(0)
	v_add_f32_e32 v32, v32, v33
	ds_bpermute_b32 v33, v67, v32
	s_waitcnt lgkmcnt(0)
	v_add_f32_e32 v32, v32, v33
	v_fmamk_f32 v32, v32, 0x3a000000, v209
	v_cmp_gt_f32_e32 vcc, s15, v32
	v_mul_f32_e32 v33, 0x4b800000, v32
	s_nop 0
	v_cndmask_b32_e32 v32, v32, v33, vcc
	v_rsq_f32_e32 v32, v32
	s_nop 0
	v_mul_f32_e32 v33, 0x45800000, v32
	v_cndmask_b32_e32 v32, v32, v33, vcc
	v_mul_f32_e32 v24, v24, v32
	s_nop 0
	v_mul_f32_e32 v33, v152, v24
	v_mul_f32_e32 v24, v25, v32
	v_mul_f32_e32 v28, v28, v32
	v_mul_f32_e32 v34, v153, v24
	v_mul_f32_e32 v24, v26, v32
	s_nop 0
	v_mul_f32_e32 v28, v156, v28
	v_mul_f32_e32 v29, v29, v32
	v_mul_f32_e32 v35, v154, v24
	v_mul_f32_e32 v24, v27, v32
	v_mul_f32_e32 v29, v157, v29
	v_mul_f32_e32 v27, v155, v24
	v_cvt_pk_bf16_f32 v24, v28, v29
	v_add_co_u32_e32 v28, vcc, s2, v52
	v_mul_f32_e32 v30, v30, v32
	v_mul_f32_e32 v31, v31, v32
	v_addc_co_u32_e32 v29, vcc, -1, v53, vcc
	v_mul_f32_e32 v30, v158, v30
	v_mul_f32_e32 v31, v159, v31
	v_cvt_pk_bf16_f32 v25, v30, v31
	v_cvt_pk_bf16_f32 v26, v33, v34
	v_cvt_pk_bf16_f32 v27, v35, v27
	global_store_dwordx4 v[28:29], v[24:27], off offset:-3072
	s_nop 0
	v_mul_f32_e32 v16, v16, v32
	v_mul_f32_e32 v20, v20, v32
	v_mul_f32_e32 v21, v21, v32
	v_mul_f32_e32 v22, v22, v32
	v_mul_f32_e32 v23, v23, v32
	v_mul_f32_e32 v8, v8, v32
	v_mul_f32_e32 v12, v12, v32
	v_mul_f32_e32 v13, v13, v32
	v_mul_f32_e32 v14, v14, v32
	v_mul_f32_e32 v15, v15, v32
	v_mul_f32_e32 v0, v0, v32
	v_mul_f32_e32 v4, v4, v32
	v_mul_f32_e32 v5, v5, v32
	v_mul_f32_e32 v6, v6, v32
	v_mul_f32_e32 v7, v7, v32
	v_lshl_add_u64 v[52:53], v[52:53], 0, s[18:19]
	s_nop 0
	v_mul_f32_e32 v24, v160, v16
	v_mul_f32_e32 v16, v17, v32
	v_mul_f32_e32 v25, v161, v16
	v_mul_f32_e32 v16, v18, v32
	v_mul_f32_e32 v26, v162, v16
	v_mul_f32_e32 v16, v19, v32
	v_mul_f32_e32 v19, v163, v16
	s_nop 0
	v_mul_f32_e32 v20, v164, v20
	v_mul_f32_e32 v21, v165, v21
	v_mul_f32_e32 v22, v166, v22
	v_mul_f32_e32 v23, v167, v23
	v_cvt_pk_bf16_f32 v16, v20, v21
	v_cvt_pk_bf16_f32 v17, v22, v23
	v_cvt_pk_bf16_f32 v18, v24, v25
	v_cvt_pk_bf16_f32 v19, v26, v19
	global_store_dwordx4 v[28:29], v[16:19], off offset:-2048
	s_nop 0
	s_nop 0
	v_mul_f32_e32 v16, v168, v8
	v_mul_f32_e32 v8, v9, v32
	v_mul_f32_e32 v17, v169, v8
	v_mul_f32_e32 v8, v10, v32
	v_mul_f32_e32 v18, v170, v8
	v_mul_f32_e32 v8, v11, v32
	v_mul_f32_e32 v11, v171, v8
	s_nop 0
	v_mul_f32_e32 v12, v172, v12
	v_mul_f32_e32 v13, v173, v13
	v_mul_f32_e32 v14, v174, v14
	v_mul_f32_e32 v15, v175, v15
	v_cvt_pk_bf16_f32 v8, v12, v13
	v_cvt_pk_bf16_f32 v9, v14, v15
	v_cvt_pk_bf16_f32 v10, v16, v17
	v_cvt_pk_bf16_f32 v11, v18, v11
	global_store_dwordx4 v[28:29], v[8:11], off offset:-1024
	s_nop 0
	s_nop 0
	v_mul_f32_e32 v8, v176, v0
	v_mul_f32_e32 v0, v1, v32
	v_mul_f32_e32 v9, v177, v0
	v_mul_f32_e32 v0, v2, v32
	v_mul_f32_e32 v10, v178, v0
	v_mul_f32_e32 v0, v3, v32
	v_mul_f32_e32 v3, v179, v0
	s_nop 0
	v_mul_f32_e32 v4, v180, v4
	v_mul_f32_e32 v5, v181, v5
	v_mul_f32_e32 v6, v182, v6
	v_mul_f32_e32 v7, v183, v7
	v_cvt_pk_bf16_f32 v0, v4, v5
	v_cvt_pk_bf16_f32 v1, v6, v7
	v_cvt_pk_bf16_f32 v2, v8, v9
	v_cvt_pk_bf16_f32 v3, v10, v3
	global_store_dwordx4 v[28:29], v[0:3], off
	s_cbranch_scc0 .LBB0_466
	s_mov_b32 s17, s6

; __device__ __forceinline__ u32x4 pack8(const float* f) { u32x4 w; w.x = pk2(f[0], f[1]); w.y = pk2(f[2], f[3]); w.z = pk2(f[4], f[5]); w.w = pk2(f[6], f[7]); return w; }
; template <bool HAS_M, bool WRITE_X, bool WRITE_HN>
; __device__ __forceinline__ void seam_rows(const float* xin, const bf16_t* mb, const float* gpost, const float* gpre, float* xout, bf16_t* hn, int gw, int NGW, int lane) {
;     for (int row = gw; row < M; row += NGW) {
;         const size_t ro = (size_t)row * DM + lane * 8;
;         float v[32];
; #pragma unroll
;         for (int s = 0; s < 4; ++s) ld8f(xin + ro + s * 512, v + s * 8);
;         if (HAS_M) {
;             float mv[32]; float ss = 0.f;
; #pragma unroll
;             for (int s = 0; s < 4; ++s) unpack8(*(const u32x4*)(mb + ro + s * 512), mv + s * 8);
; #pragma unroll
;             for (int i = 0; i < 32; ++i) ss += mv[i] * mv[i];
;             const float r1 = rsqrtf(wave_sum(ss) * (1.f / 2048.f) + 1e-6f);
; #pragma unroll
;             for (int s = 0; s < 4; ++s) { float g[8]; ld8f(gpost + s * 512 + lane * 8, g);
; #pragma unroll
;                 for (int i = 0; i < 8; ++i) v[s * 8 + i] += mv[s * 8 + i] * r1 * g[i]; }
;         }
;         if (WRITE_X) {
; #pragma unroll
;             for (int s = 0; s < 4; ++s) { *(f32x4*)(xout + ro + s * 512) = (f32x4){v[s * 8], v[s * 8 + 1], v[s * 8 + 2], v[s * 8 + 3]}; *(f32x4*)(xout + ro + s * 512 + 4) = (f32x4){v[s * 8 + 4], v[s * 8 + 5], v[s * 8 + 6], v[s * 8 + 7]}; }
;         }
;         if (WRITE_HN) {
;             float ss = 0.f;
; #pragma unroll
;             for (int i = 0; i < 32; ++i) ss += v[i] * v[i];
;             const float r2 = rsqrtf(wave_sum(ss) * (1.f / 2048.f) + 1e-6f);
; #pragma unroll
;             for (int s = 0; s < 4; ++s) { float g[8], o[8]; ld8f(gpre + s * 512 + lane * 8, g);
; #pragma unroll
;                 for (int i = 0; i < 8; ++i) o[i] = v[s * 8 + i] * r2 * g[i];
;                 *(u32x4*)(hn + ro + s * 512) = pack8(o); }
.LBB0_788:
	global_load_dwordx4 v[24:27], v[14:15], off offset:-4096
	global_load_dwordx4 v[0:3], v[14:15], off offset:2064
	global_load_dwordx4 v[28:31], v[14:15], off offset:-4080
	global_load_dwordx4 v[32:35], v[14:15], off offset:-2048
	global_load_dwordx4 v[36:39], v[14:15], off offset:-2032
	global_load_dwordx4 v[40:43], v[14:15], off
	global_load_dwordx4 v[44:47], v[14:15], off offset:16
	global_load_dwordx4 v[4:7], v[14:15], off offset:2048
	global_load_dwordx4 v[48:51], v[8:9], off offset:16
	global_load_dwordx4 v[52:55], v[8:9], off
	s_add_i32 s10, s10, s16
	v_lshl_add_u64 v[14:15], v[14:15], 0, s[0:1]
	s_cmpk_gt_i32 s10, 0x3fff
	s_waitcnt vmcnt(9)
	v_mul_f32_e32 v60, v25, v25
	v_fmac_f32_e32 v60, v24, v24
	v_fmac_f32_e32 v60, v26, v26
	v_fmac_f32_e32 v60, v27, v27
	s_waitcnt vmcnt(7)
	v_fmac_f32_e32 v60, v28, v28
	v_fmac_f32_e32 v60, v29, v29
	v_fmac_f32_e32 v60, v30, v30
	v_fmac_f32_e32 v60, v31, v31
	s_waitcnt vmcnt(6)
	v_fmac_f32_e32 v60, v32, v32
	v_fmac_f32_e32 v60, v33, v33
	v_fmac_f32_e32 v60, v34, v34
	v_fmac_f32_e32 v60, v35, v35
	s_waitcnt vmcnt(5)
	v_fmac_f32_e32 v60, v36, v36
	v_fmac_f32_e32 v60, v37, v37
	v_fmac_f32_e32 v60, v38, v38
	v_fmac_f32_e32 v60, v39, v39
	s_waitcnt vmcnt(4)
	v_fmac_f32_e32 v60, v40, v40
	v_fmac_f32_e32 v60, v41, v41
	v_fmac_f32_e32 v60, v42, v42
	v_fmac_f32_e32 v60, v43, v43
	s_waitcnt vmcnt(3)
	v_fmac_f32_e32 v60, v44, v44
	v_fmac_f32_e32 v60, v45, v45
	v_fmac_f32_e32 v60, v46, v46
	v_fmac_f32_e32 v60, v47, v47
	s_waitcnt vmcnt(2)
	v_fmac_f32_e32 v60, v4, v4
	v_fmac_f32_e32 v60, v5, v5
	v_fmac_f32_e32 v60, v6, v6
	v_pk_mul_f32 v[58:59], v[0:1], v[0:1]
	v_fmac_f32_e32 v60, v7, v7
	v_add_f32_e32 v58, v58, v60
	v_pk_mul_f32 v[56:57], v[2:3], v[2:3]
	v_add_f32_e32 v58, v59, v58
	v_add_f32_e32 v56, v56, v58
	v_add_f32_e32 v56, v57, v56
	s_nop 1
	v_add_f32_dpp v56, v56, v56 quad_perm:[1,0,3,2] row_mask:0xf bank_mask:0xf
	s_nop 1
	v_add_f32_dpp v56, v56, v56 quad_perm:[2,3,0,1] row_mask:0xf bank_mask:0xf
	s_nop 1
	v_add_f32_dpp v56, v56, v56 row_half_mirror row_mask:0xf bank_mask:0xf
	s_nop 1
	v_add_f32_dpp v56, v56, v56 row_mirror row_mask:0xf bank_mask:0xf
	ds_bpermute_b32 v57, v22, v56
	s_waitcnt lgkmcnt(0)
	v_add_f32_e32 v56, v56, v57
	ds_bpermute_b32 v57, v23, v56
	s_waitcnt lgkmcnt(0)
	v_add_f32_e32 v56, v56, v57
	v_fmamk_f32 v56, v56, 0x3a000000, v209
	v_mul_f32_e32 v57, 0x4b800000, v56
	v_cmp_gt_f32_e32 vcc, s15, v56
	s_nop 1
	v_cndmask_b32_e32 v56, v56, v57, vcc
	v_rsq_f32_e32 v56, v56
	s_nop 0
	v_mul_f32_e32 v57, 0x45800000, v56
	v_cndmask_b32_e32 v56, v56, v57, vcc
	v_mul_f32_e32 v24, v24, v56
	v_mul_f32_e32 v25, v25, v56
	v_mul_f32_e32 v26, v26, v56
	v_mul_f32_e32 v27, v27, v56
	v_mul_f32_e32 v28, v28, v56
	v_mul_f32_e32 v29, v29, v56
	v_mul_f32_e32 v30, v30, v56
	v_mul_f32_e32 v31, v31, v56
	s_waitcnt vmcnt(0)
	v_mul_f32_e32 v24, v52, v24
	v_mul_f32_e32 v25, v53, v25
	v_mul_f32_e32 v26, v54, v26
	v_mul_f32_e32 v27, v55, v27
	v_mul_f32_e32 v28, v48, v28
	v_mul_f32_e32 v29, v49, v29
	v_mul_f32_e32 v30, v50, v30
	v_mul_f32_e32 v31, v51, v31
	v_cvt_pk_bf16_f32 v24, v24, v25
	v_cvt_pk_bf16_f32 v25, v26, v27
	v_cvt_pk_bf16_f32 v26, v28, v29
	v_cvt_pk_bf16_f32 v27, v30, v31
	global_store_dwordx4 v[16:17], v[24:27], off offset:-2048
	s_nop 0
	v_mul_f32_e32 v32, v32, v56
	v_mul_f32_e32 v33, v33, v56
	v_mul_f32_e32 v34, v34, v56
	v_mul_f32_e32 v35, v35, v56
	v_mul_f32_e32 v36, v36, v56
	v_mul_f32_e32 v37, v37, v56
	v_mul_f32_e32 v38, v38, v56
	v_mul_f32_e32 v39, v39, v56
	v_mul_f32_e32 v3, v3, v56
	v_mul_f32_e32 v4, v4, v56
	v_mul_f32_e32 v5, v5, v56
	v_mul_f32_e32 v6, v6, v56
	v_mul_f32_e32 v7, v7, v56
	v_mul_f32_e32 v0, v0, v56
	v_mul_f32_e32 v1, v1, v56
	v_mul_f32_e32 v2, v2, v56
	s_nop 0
	v_mul_f32_e32 v24, v152, v32
	v_mul_f32_e32 v25, v153, v33
	v_mul_f32_e32 v26, v154, v34
	v_mul_f32_e32 v27, v155, v35
	s_nop 0
	v_mul_f32_e32 v28, v156, v36
	v_mul_f32_e32 v29, v157, v37
	v_mul_f32_e32 v30, v158, v38
	v_mul_f32_e32 v31, v159, v39
	v_cvt_pk_bf16_f32 v24, v24, v25
	v_cvt_pk_bf16_f32 v25, v26, v27
	v_cvt_pk_bf16_f32 v26, v28, v29
	v_cvt_pk_bf16_f32 v27, v30, v31
	global_store_dwordx4 v[16:17], v[24:27], off offset:-1024
	s_nop 0
	v_mul_f32_e32 v32, v40, v56
	v_mul_f32_e32 v33, v41, v56
	v_mul_f32_e32 v34, v42, v56
	v_mul_f32_e32 v35, v43, v56
	v_mul_f32_e32 v36, v44, v56
	v_mul_f32_e32 v37, v45, v56
	v_mul_f32_e32 v38, v46, v56
	v_mul_f32_e32 v39, v47, v56
	s_nop 0
	v_mul_f32_e32 v24, v160, v32
	v_mul_f32_e32 v25, v161, v33
	v_mul_f32_e32 v26, v162, v34
	v_mul_f32_e32 v27, v163, v35
	s_nop 0
	v_mul_f32_e32 v28, v164, v36
	v_mul_f32_e32 v29, v165, v37
	v_mul_f32_e32 v30, v166, v38
	v_mul_f32_e32 v31, v167, v39
	v_cvt_pk_bf16_f32 v24, v24, v25
	v_cvt_pk_bf16_f32 v25, v26, v27
	v_cvt_pk_bf16_f32 v26, v28, v29
	v_cvt_pk_bf16_f32 v27, v30, v31
	global_store_dwordx4 v[16:17], v[24:27], off
	s_nop 0
	s_nop 0
	v_mul_f32_e32 v4, v168, v4
	s_nop 0
	v_mul_f32_e32 v3, v175, v3
	v_mul_f32_e32 v5, v169, v5
	v_mul_f32_e32 v6, v170, v6
	v_mul_f32_e32 v7, v171, v7
	v_mul_f32_e32 v24, v172, v0
	v_mul_f32_e32 v25, v173, v1
	v_mul_f32_e32 v26, v174, v2
	v_cvt_pk_bf16_f32 v0, v4, v5
	v_cvt_pk_bf16_f32 v1, v6, v7
	v_cvt_pk_bf16_f32 v2, v24, v25
	v_cvt_pk_bf16_f32 v3, v26, v3
	global_store_dwordx4 v[16:17], v[0:3], off offset:1024
	v_lshl_add_u64 v[16:17], v[16:17], 0, s[4:5]
	s_cbranch_scc0 .LBB0_788
